# gate-weight staging in one round trip; norm row loop: second-half gain/mod loads issued with the first, DPP row sum
# speedup vs baseline: 1.0026x; 1.0026x over previous
.LBB0_211:
	v_lshl_add_u64 v[36:37], s[92:93], 0, v[6:7]
	global_load_dwordx4 v[16:19], v[2:3], off offset:16
	global_load_dwordx4 v[20:23], v[2:3], off
	global_load_dwordx4 v[24:27], v[36:37], off
	global_load_dwordx4 v[28:31], v[36:37], off offset:16
	global_load_dwordx4 v[32:35], v[36:37], off offset:2048
	s_nop 0
	global_load_dwordx4 v[36:39], v[36:37], off offset:2064
	v_min_i32_e32 v1, 0x4000, v0
	v_lshl_add_u64 v[40:41], s[92:93], 0, v[4:5]
	v_ashrrev_i32_e32 v1, 11, v1
	v_add_co_u32_e32 v56, vcc, s28, v40
	v_mul_i32_i24_e32 v40, 0x9000, v1
	s_nop 0
	v_addc_co_u32_e32 v57, vcc, 0, v41, vcc
	v_mul_hi_i32_i24_e32 v41, 0x9000, v1
	v_lshl_add_u64 v[40:41], s[16:17], 0, v[40:41]
	v_lshl_add_u64 v[48:49], v[40:41], 0, s[6:7]
	v_mov_b32_e32 v9, v97
	v_lshl_add_u64 v[58:59], v[40:41], 0, v[96:97]
	v_lshl_add_u64 v[52:53], v[48:49], 0, v[96:97]
	global_load_dwordx4 v[40:43], v[58:59], off offset:16
	global_load_dwordx4 v[44:47], v[58:59], off
	v_lshl_add_u64 v[60:61], v[48:49], 0, v[8:9]
	global_load_dwordx4 v[48:51], v[52:53], off offset:16
	s_nop 0
	global_load_dwordx4 v[52:55], v[52:53], off
	global_load_dwordx4 v[86:89], v[2:3], off offset:2048
	global_load_dwordx4 v[90:93], v[60:61], off
	global_load_dwordx4 v[98:101], v[2:3], off offset:2064
	global_load_dwordx4 v[106:109], v[60:61], off offset:16
	global_load_dwordx4 v[110:113], v[58:59], off offset:2048
	global_load_dwordx4 v[114:117], v[58:59], off offset:2064
	v_add_u32_e32 v0, s8, v0
	v_lshl_add_u64 v[4:5], v[4:5], 0, s[30:31]
	v_lshl_add_u64 v[6:7], v[6:7], 0, s[14:15]
	s_waitcnt vmcnt(13)
	v_mov_b32_e32 v68, v25
	s_waitcnt vmcnt(12)
	v_mov_b32_e32 v69, v29
	v_mov_b32_e32 v66, v24
	v_mov_b32_e32 v67, v28
	s_waitcnt vmcnt(11)
	v_mov_b32_e32 v76, v33
	s_waitcnt vmcnt(10)
	v_mov_b32_e32 v77, v37
	v_pk_mul_f32 v[68:69], v[68:69], v[68:69]
	v_mov_b32_e32 v62, v26
	v_mov_b32_e32 v63, v30
	v_mov_b32_e32 v74, v32
	v_mov_b32_e32 v75, v36
	v_pk_mul_f32 v[76:77], v[76:77], v[76:77]
	v_pk_fma_f32 v[66:67], v[66:67], v[66:67], v[68:69]
	v_mov_b32_e32 v64, v27
	v_mov_b32_e32 v65, v31
	v_mov_b32_e32 v70, v34
	v_mov_b32_e32 v71, v38
	v_pk_fma_f32 v[68:69], v[74:75], v[74:75], v[76:77]
	v_pk_fma_f32 v[62:63], v[62:63], v[62:63], v[66:67]
	v_mov_b32_e32 v72, v35
	v_mov_b32_e32 v73, v39
	v_pk_fma_f32 v[66:67], v[70:71], v[70:71], v[68:69]
	v_pk_fma_f32 v[62:63], v[64:65], v[64:65], v[62:63]
	v_pk_fma_f32 v[64:65], v[72:73], v[72:73], v[66:67]
	v_add_f32_e32 v1, v62, v63
	v_add_f32_e32 v1, v1, v64
	v_add_f32_e32 v1, v1, v65
	v_mov_b32_e32 v9, v1
	v_mov_b32_e32 v255, v1
	s_nop 1
	v_permlane32_swap_b32_e32 v9, v255
	s_nop 1
	v_mov_b32_dpp v9, v255 quad_perm:[0,1,2,3] row_mask:0x3 bank_mask:0xf
	s_waitcnt vmcnt(7)
	v_pk_add_f32 v[48:49], v[48:49], 1.0 op_sel_hi:[1,0]
	s_waitcnt vmcnt(6)
	v_pk_add_f32 v[54:55], v[54:55], 1.0 op_sel_hi:[1,0]
	v_pk_add_f32 v[52:53], v[52:53], 1.0 op_sel_hi:[1,0]
	v_pk_add_f32 v[50:51], v[50:51], 1.0 op_sel_hi:[1,0]
	s_waitcnt lgkmcnt(0)
	v_add_f32_e32 v1, v1, v9
	v_mov_b32_e32 v9, v1
	v_mov_b32_e32 v255, v1
	s_nop 1
	v_permlane16_swap_b32_e32 v9, v255
	s_nop 1
	v_mov_b32_dpp v9, v255 quad_perm:[0,1,2,3] row_mask:0x5 bank_mask:0xf
	s_nop 0
	v_add_f32_e32 v1, v1, v9
	s_nop 1
	v_mov_b32_dpp v9, v1 row_ror:8 row_mask:0xf bank_mask:0xf
	s_nop 0
	v_add_f32_e32 v1, v1, v9
	s_nop 1
	v_mov_b32_dpp v9, v1 row_shl:4 row_mask:0xf bank_mask:0x5
	v_mov_b32_dpp v9, v1 row_shr:4 row_mask:0xf bank_mask:0xa
	s_nop 0
	v_add_f32_e32 v1, v1, v9
	s_nop 1
	v_mov_b32_dpp v9, v1 quad_perm:[2,3,0,1] row_mask:0xf bank_mask:0xf
	s_nop 0
	v_add_f32_e32 v1, v1, v9
	s_nop 1
	v_mov_b32_dpp v9, v1 quad_perm:[1,0,3,2] row_mask:0xf bank_mask:0xf
	s_nop 0
	v_add_f32_e32 v1, v1, v9
	v_fmamk_f32 v1, v1, 0x3a800000, v163
	v_mul_f32_e32 v9, 0x4b800000, v1
	v_cmp_gt_f32_e32 vcc, s86, v1
	s_nop 1
	v_cndmask_b32_e32 v1, v1, v9, vcc
	v_rsq_f32_e32 v1, v1
	s_nop 0
	v_mul_f32_e32 v9, 0x45800000, v1
	v_cndmask_b32_e32 v62, v1, v9, vcc
	v_pk_mul_f32 v[24:25], v[24:25], v[62:63] op_sel_hi:[1,0]
	v_pk_mul_f32 v[26:27], v[26:27], v[62:63] op_sel_hi:[1,0]
	v_pk_mul_f32 v[28:29], v[28:29], v[62:63] op_sel_hi:[1,0]
	v_pk_mul_f32 v[30:31], v[30:31], v[62:63] op_sel_hi:[1,0]
	v_pk_mul_f32 v[20:21], v[20:21], v[24:25]
	v_pk_mul_f32 v[22:23], v[22:23], v[26:27]
	v_pk_mul_f32 v[16:17], v[28:29], v[16:17]
	v_pk_mul_f32 v[18:19], v[30:31], v[18:19]
	v_pk_fma_f32 v[20:21], v[52:53], v[20:21], v[44:45]
	v_pk_fma_f32 v[22:23], v[54:55], v[22:23], v[46:47]
	v_pk_fma_f32 v[24:25], v[16:17], v[48:49], v[40:41]
	v_pk_fma_f32 v[26:27], v[18:19], v[50:51], v[42:43]
	v_cvt_pk_bf16_f32 v16, v20, v21
	v_cvt_pk_bf16_f32 v17, v22, v23
	v_cvt_pk_bf16_f32 v18, v24, v25
	v_cvt_pk_bf16_f32 v19, v26, v27
	global_store_dwordx4 v[56:57], v[16:19], off
	s_nop 0
	v_pk_mul_f32 v[32:33], v[32:33], v[62:63] op_sel_hi:[1,0]
	v_pk_mul_f32 v[34:35], v[34:35], v[62:63] op_sel_hi:[1,0]
	v_pk_mul_f32 v[36:37], v[36:37], v[62:63] op_sel_hi:[1,0]
	v_pk_mul_f32 v[38:39], v[38:39], v[62:63] op_sel_hi:[1,0]
	v_cmp_lt_i32_e32 vcc, s29, v0
	s_or_b64 s[2:3], vcc, s[2:3]
	s_waitcnt vmcnt(6)
	v_pk_mul_f32 v[16:17], v[32:33], v[86:87]
	s_waitcnt vmcnt(5)
	v_pk_add_f32 v[20:21], v[90:91], 1.0 op_sel_hi:[1,0]
	v_pk_mul_f32 v[18:19], v[34:35], v[88:89]
	v_pk_add_f32 v[22:23], v[92:93], 1.0 op_sel_hi:[1,0]
	s_waitcnt vmcnt(4)
	v_pk_mul_f32 v[24:25], v[36:37], v[98:99]
	s_waitcnt vmcnt(3)
	v_pk_add_f32 v[28:29], v[106:107], 1.0 op_sel_hi:[1,0]
	v_pk_mul_f32 v[26:27], v[38:39], v[100:101]
	v_pk_add_f32 v[30:31], v[108:109], 1.0 op_sel_hi:[1,0]
	s_waitcnt vmcnt(2)
	v_pk_fma_f32 v[16:17], v[16:17], v[20:21], v[110:111]
	v_pk_fma_f32 v[18:19], v[18:19], v[22:23], v[112:113]
	s_waitcnt vmcnt(1)
	v_pk_fma_f32 v[20:21], v[24:25], v[28:29], v[114:115]
	v_pk_fma_f32 v[22:23], v[26:27], v[30:31], v[116:117]
	v_cvt_pk_bf16_f32 v16, v16, v17
	v_cvt_pk_bf16_f32 v17, v18, v19
	v_cvt_pk_bf16_f32 v18, v20, v21
	v_cvt_pk_bf16_f32 v19, v22, v23
	global_store_dwordx4 v[56:57], v[16:19], off offset:1024
	s_andn2_b64 exec, exec, s[2:3]
	s_cbranch_execnz .LBB0_211

.LBB0_390:
	v_min_i32_e32 v0, 0x4000, v12
	v_ashrrev_i32_e32 v0, 11, v0
	v_mul_hi_i32_i24_e32 v1, 0x9000, v0
	v_mul_i32_i24_e32 v0, 0x9000, v0
	v_lshl_add_u64 v[0:1], s[2:3], 0, v[0:1]
	v_lshl_add_u64 v[26:27], v[0:1], 0, s[10:11]
	v_lshl_add_u64 v[58:59], s[92:93], 0, v[20:21]
	v_lshl_add_u64 v[4:5], v[26:27], 0, v[96:97]
	v_lshl_add_u64 v[24:25], v[0:1], 0, v[96:97]
	global_load_dwordx4 v[38:41], v[58:59], off offset:16
	global_load_dwordx4 v[8:11], v[58:59], off
	global_load_dwordx4 v[42:45], v[16:17], off offset:16
	global_load_dwordx4 v[46:49], v[16:17], off
	global_load_dwordx4 v[50:53], v[24:25], off offset:16
	global_load_dwordx4 v[54:57], v[24:25], off
	global_load_dwordx4 v[0:3], v[4:5], off offset:16
	s_nop 0
	global_load_dwordx4 v[4:7], v[4:5], off
	v_mov_b32_e32 v23, v97
	v_lshl_add_u64 v[26:27], v[26:27], 0, v[22:23]
	v_lshl_add_u64 v[30:31], s[92:93], 0, v[18:19]
	v_add_u32_e32 v12, s8, v12
	v_lshl_add_u64 v[18:19], v[18:19], 0, s[30:31]
	v_lshl_add_u64 v[20:21], v[20:21], 0, s[14:15]
	s_waitcnt vmcnt(7)
	v_mov_b32_e32 v67, v39
	s_waitcnt vmcnt(6)
	v_mov_b32_e32 v66, v9
	v_pk_mul_f32 v[66:67], v[66:67], v[66:67]
	s_waitcnt vmcnt(1)
	v_pk_add_f32 v[60:61], v[0:1], 1.0 op_sel_hi:[1,0]
	s_waitcnt vmcnt(0)
	v_pk_add_f32 v[62:63], v[6:7], 1.0 op_sel_hi:[1,0]
	v_mov_b32_e32 v6, v8
	v_mov_b32_e32 v7, v38
	v_mov_b32_e32 v0, v10
	v_mov_b32_e32 v1, v40
	v_pk_fma_f32 v[6:7], v[6:7], v[6:7], v[66:67]
	v_pk_add_f32 v[64:65], v[4:5], 1.0 op_sel_hi:[1,0]
	v_mov_b32_e32 v4, v11
	v_mov_b32_e32 v5, v41
	v_pk_fma_f32 v[0:1], v[0:1], v[0:1], v[6:7]
	v_pk_add_f32 v[68:69], v[2:3], 1.0 op_sel_hi:[1,0]
	v_pk_fma_f32 v[66:67], v[4:5], v[4:5], v[0:1]
	global_load_dwordx4 v[0:3], v[58:59], off offset:2064
	global_load_dwordx4 v[4:7], v[58:59], off offset:2048
	global_load_dwordx4 v[86:89], v[14:15], off offset:16
	global_load_dwordx4 v[90:93], v[14:15], off
	global_load_dwordx4 v[98:101], v[24:25], off offset:2064
	global_load_dwordx4 v[106:109], v[24:25], off offset:2048
	global_load_dwordx4 v[110:113], v[26:27], off offset:16
	global_load_dwordx4 v[114:117], v[26:27], off
	v_add_f32_e32 v13, v66, v67
	s_waitcnt vmcnt(7)
	v_mov_b32_e32 v75, v1
	s_waitcnt vmcnt(6)
	v_mov_b32_e32 v74, v5
	v_mov_b32_e32 v72, v4
	v_mov_b32_e32 v73, v0
	v_pk_mul_f32 v[74:75], v[74:75], v[74:75]
	v_mov_b32_e32 v58, v6
	v_mov_b32_e32 v59, v2
	v_pk_fma_f32 v[72:73], v[72:73], v[72:73], v[74:75]
	v_mov_b32_e32 v70, v7
	v_mov_b32_e32 v71, v3
	v_pk_fma_f32 v[58:59], v[58:59], v[58:59], v[72:73]
	s_nop 0
	v_pk_fma_f32 v[58:59], v[70:71], v[70:71], v[58:59]
	s_nop 0
	v_add_f32_e32 v13, v13, v58
	v_add_f32_e32 v13, v13, v59
	v_mov_b32_e32 v23, v13
	v_mov_b32_e32 v255, v13
	s_nop 1
	v_permlane32_swap_b32_e32 v23, v255
	s_nop 1
	v_mov_b32_dpp v23, v255 quad_perm:[0,1,2,3] row_mask:0x3 bank_mask:0xf
	s_waitcnt lgkmcnt(0)
	v_add_f32_e32 v13, v13, v23
	v_mov_b32_e32 v23, v13
	v_mov_b32_e32 v255, v13
	s_nop 1
	v_permlane16_swap_b32_e32 v23, v255
	s_nop 1
	v_mov_b32_dpp v23, v255 quad_perm:[0,1,2,3] row_mask:0x5 bank_mask:0xf
	s_nop 0
	v_add_f32_e32 v13, v13, v23
	s_nop 1
	v_mov_b32_dpp v23, v13 row_ror:8 row_mask:0xf bank_mask:0xf
	s_nop 0
	v_add_f32_e32 v13, v13, v23
	s_nop 1
	v_mov_b32_dpp v23, v13 row_shl:4 row_mask:0xf bank_mask:0x5
	v_mov_b32_dpp v23, v13 row_shr:4 row_mask:0xf bank_mask:0xa
	s_nop 0
	v_add_f32_e32 v13, v13, v23
	s_nop 1
	v_mov_b32_dpp v23, v13 quad_perm:[2,3,0,1] row_mask:0xf bank_mask:0xf
	s_nop 0
	v_add_f32_e32 v13, v13, v23
	s_nop 1
	v_mov_b32_dpp v23, v13 quad_perm:[1,0,3,2] row_mask:0xf bank_mask:0xf
	s_nop 0
	v_add_f32_e32 v13, v13, v23
	v_fmamk_f32 v13, v13, 0x3a800000, v163
	v_cmp_gt_f32_e32 vcc, s86, v13
	v_mul_f32_e32 v23, 0x4b800000, v13
	s_nop 0
	v_cndmask_b32_e32 v13, v13, v23, vcc
	v_rsq_f32_e32 v13, v13
	s_nop 0
	v_mul_f32_e32 v23, 0x45800000, v13
	v_cndmask_b32_e32 v28, v13, v23, vcc
	v_pk_mul_f32 v[8:9], v[8:9], v[28:29] op_sel_hi:[1,0]
	v_pk_mul_f32 v[10:11], v[10:11], v[28:29] op_sel_hi:[1,0]
	v_pk_mul_f32 v[8:9], v[46:47], v[8:9]
	v_pk_mul_f32 v[10:11], v[48:49], v[10:11]
	v_pk_fma_f32 v[8:9], v[64:65], v[8:9], v[54:55]
	v_pk_fma_f32 v[10:11], v[62:63], v[10:11], v[56:57]
	v_cvt_pk_bf16_f32 v8, v8, v9
	v_cvt_pk_bf16_f32 v9, v10, v11
	v_pk_mul_f32 v[10:11], v[38:39], v[28:29] op_sel_hi:[1,0]
	v_pk_mul_f32 v[38:39], v[40:41], v[28:29] op_sel_hi:[1,0]
	v_pk_mul_f32 v[10:11], v[10:11], v[42:43]
	v_pk_mul_f32 v[38:39], v[38:39], v[44:45]
	v_pk_fma_f32 v[10:11], v[10:11], v[60:61], v[50:51]
	v_pk_fma_f32 v[38:39], v[38:39], v[68:69], v[52:53]
	v_add_co_u32_e32 v30, vcc, s28, v30
	v_cvt_pk_bf16_f32 v10, v10, v11
	v_cvt_pk_bf16_f32 v11, v38, v39
	v_addc_co_u32_e32 v31, vcc, 0, v31, vcc
	global_store_dwordx4 v[30:31], v[8:11], off
	s_nop 0
	s_nop 0
	v_pk_mul_f32 v[4:5], v[4:5], v[28:29] op_sel_hi:[1,0]
	v_pk_mul_f32 v[6:7], v[6:7], v[28:29] op_sel_hi:[1,0]
	v_pk_mul_f32 v[0:1], v[0:1], v[28:29] op_sel_hi:[1,0]
	v_pk_mul_f32 v[2:3], v[2:3], v[28:29] op_sel_hi:[1,0]
	v_cmp_lt_i32_e32 vcc, s29, v12
	s_or_b64 s[6:7], vcc, s[6:7]
	s_waitcnt vmcnt(6)
	v_pk_mul_f32 v[0:1], v[0:1], v[86:87]
	s_waitcnt vmcnt(5)
	v_pk_mul_f32 v[4:5], v[4:5], v[90:91]
	v_pk_mul_f32 v[6:7], v[6:7], v[92:93]
	v_pk_mul_f32 v[2:3], v[2:3], v[88:89]
	s_waitcnt vmcnt(1)
	v_pk_add_f32 v[24:25], v[114:115], 1.0 op_sel_hi:[1,0]
	s_nop 0
	v_pk_fma_f32 v[4:5], v[4:5], v[24:25], v[106:107]
	v_pk_add_f32 v[24:25], v[116:117], 1.0 op_sel_hi:[1,0]
	v_cvt_pk_bf16_f32 v4, v4, v5
	v_pk_fma_f32 v[6:7], v[6:7], v[24:25], v[108:109]
	s_nop 0
	v_cvt_pk_bf16_f32 v5, v6, v7
	v_pk_add_f32 v[6:7], v[110:111], 1.0 op_sel_hi:[1,0]
	s_nop 0
	v_pk_fma_f32 v[0:1], v[0:1], v[6:7], v[98:99]
	v_pk_add_f32 v[6:7], v[112:113], 1.0 op_sel_hi:[1,0]
	s_nop 0
	v_pk_fma_f32 v[2:3], v[2:3], v[6:7], v[100:101]
	v_cvt_pk_bf16_f32 v6, v0, v1
	v_cvt_pk_bf16_f32 v7, v2, v3
	global_store_dwordx4 v[30:31], v[4:7], off offset:1024
	s_andn2_b64 exec, exec, s[6:7]
	s_cbranch_execnz .LBB0_390

.LBB0_578:
	v_add_u32_e32 v2, s4, v0
	s_addk_i32 s4, 0x800
	v_mov_b32_e32 v222, v2
	v_ashrrev_i32_e32 v223, 31, v222
	v_lshlrev_b64 v[222:223], 2, v[222:223]
	v_lshl_add_u64 v[224:225], s[0:1], 0, v[222:223]
	global_load_dword v206, v[224:225], off
	global_load_dword v207, v[224:225], off offset:256
	v_lshl_add_u64 v[224:225], s[6:7], 0, v[222:223]
	global_load_dword v208, v[224:225], off
	global_load_dword v209, v[224:225], off offset:256
	v_add_u32_e32 v222, 0x200, v2
	v_ashrrev_i32_e32 v223, 31, v222
	v_lshlrev_b64 v[222:223], 2, v[222:223]
	v_lshl_add_u64 v[224:225], s[0:1], 0, v[222:223]
	global_load_dword v210, v[224:225], off
	global_load_dword v211, v[224:225], off offset:256
	v_lshl_add_u64 v[224:225], s[6:7], 0, v[222:223]
	global_load_dword v212, v[224:225], off
	global_load_dword v213, v[224:225], off offset:256
	v_add_u32_e32 v222, 0x400, v2
	v_ashrrev_i32_e32 v223, 31, v222
	v_lshlrev_b64 v[222:223], 2, v[222:223]
	v_lshl_add_u64 v[224:225], s[0:1], 0, v[222:223]
	global_load_dword v214, v[224:225], off
	global_load_dword v215, v[224:225], off offset:256
	v_lshl_add_u64 v[224:225], s[6:7], 0, v[222:223]
	global_load_dword v216, v[224:225], off
	global_load_dword v217, v[224:225], off offset:256
	v_add_u32_e32 v222, 0x600, v2
	v_ashrrev_i32_e32 v223, 31, v222
	v_lshlrev_b64 v[222:223], 2, v[222:223]
	v_lshl_add_u64 v[224:225], s[0:1], 0, v[222:223]
	global_load_dword v218, v[224:225], off
	global_load_dword v219, v[224:225], off offset:256
	v_lshl_add_u64 v[224:225], s[6:7], 0, v[222:223]
	global_load_dword v220, v[224:225], off
	global_load_dword v221, v[224:225], off offset:256
	v_add_u32_e32 v2, s4, v0
	s_addk_i32 s4, 0x800
	v_mov_b32_e32 v222, v2
	v_ashrrev_i32_e32 v223, 31, v222
	v_lshlrev_b64 v[222:223], 2, v[222:223]
	v_lshl_add_u64 v[224:225], s[0:1], 0, v[222:223]
	global_load_dword v10, v[224:225], off
	global_load_dword v11, v[224:225], off offset:256
	v_lshl_add_u64 v[224:225], s[6:7], 0, v[222:223]
	global_load_dword v12, v[224:225], off
	global_load_dword v13, v[224:225], off offset:256
	v_add_u32_e32 v222, 0x200, v2
	v_ashrrev_i32_e32 v223, 31, v222
	v_lshlrev_b64 v[222:223], 2, v[222:223]
	v_lshl_add_u64 v[224:225], s[0:1], 0, v[222:223]
	global_load_dword v14, v[224:225], off
	global_load_dword v15, v[224:225], off offset:256
	v_lshl_add_u64 v[224:225], s[6:7], 0, v[222:223]
	global_load_dword v16, v[224:225], off
	global_load_dword v17, v[224:225], off offset:256
	v_add_u32_e32 v222, 0x400, v2
	v_ashrrev_i32_e32 v223, 31, v222
	v_lshlrev_b64 v[222:223], 2, v[222:223]
	v_lshl_add_u64 v[224:225], s[0:1], 0, v[222:223]
	global_load_dword v18, v[224:225], off
	global_load_dword v19, v[224:225], off offset:256
	v_lshl_add_u64 v[224:225], s[6:7], 0, v[222:223]
	global_load_dword v20, v[224:225], off
	global_load_dword v21, v[224:225], off offset:256
	v_add_u32_e32 v222, 0x600, v2
	v_ashrrev_i32_e32 v223, 31, v222
	v_lshlrev_b64 v[222:223], 2, v[222:223]
	v_lshl_add_u64 v[224:225], s[0:1], 0, v[222:223]
	global_load_dword v22, v[224:225], off
	global_load_dword v23, v[224:225], off offset:256
	v_lshl_add_u64 v[224:225], s[6:7], 0, v[222:223]
	global_load_dword v24, v[224:225], off
	global_load_dword v25, v[224:225], off offset:256
	v_add_u32_e32 v9, 0x2400, v1
	s_waitcnt vmcnt(16)
	v_cvt_pk_bf16_f32 v226, v206, v207
	v_cvt_pk_bf16_f32 v230, v208, v209
	v_cvt_pk_bf16_f32 v227, v210, v211
	v_cvt_pk_bf16_f32 v231, v212, v213
	v_cvt_pk_bf16_f32 v228, v214, v215
	v_cvt_pk_bf16_f32 v232, v216, v217
	v_cvt_pk_bf16_f32 v229, v218, v219
	v_cvt_pk_bf16_f32 v233, v220, v221
	ds_write2_b32 v1, v226, v227 offset1:4
	ds_write2_b32 v9, v230, v231 offset1:4
	ds_write2_b32 v1, v228, v229 offset0:8 offset1:12
	ds_write2_b32 v9, v232, v233 offset0:8 offset1:12
	v_add_u32_e32 v1, 64, v1
	v_add_u32_e32 v9, 0x2400, v1
	s_waitcnt vmcnt(0)
	v_cvt_pk_bf16_f32 v226, v10, v11
	v_cvt_pk_bf16_f32 v230, v12, v13
	v_cvt_pk_bf16_f32 v227, v14, v15
	v_cvt_pk_bf16_f32 v231, v16, v17
	v_cvt_pk_bf16_f32 v228, v18, v19
	v_cvt_pk_bf16_f32 v232, v20, v21
	v_cvt_pk_bf16_f32 v229, v22, v23
	v_cvt_pk_bf16_f32 v233, v24, v25
	ds_write2_b32 v1, v226, v227 offset1:4
	ds_write2_b32 v9, v230, v231 offset1:4
	ds_write2_b32 v1, v228, v229 offset0:8 offset1:12
	ds_write2_b32 v9, v232, v233 offset0:8 offset1:12
	v_add_u32_e32 v1, 64, v1
	s_cmpk_eq_i32 s4, 0x1000
	v_and_b32_e32 v71, 31, v51
	v_mul_u32_u24_e32 v0, 0x48, v71
	v_lshrrev_b32_e32 v1, 1, v51
	v_lshlrev_b32_e32 v0, 1, v0
	v_and_b32_e32 v1, 16, v1
	s_movk_i32 s0, 0x1200
	v_add3_u32 v67, 0, v0, v1
	v_mov_b32_e32 v0, 0
	v_mul_lo_u32 v65, v64, s0
	s_mov_b32 s0, -16
	v_mov_b32_e32 v1, v0
	v_mov_b32_e32 v2, v0
	v_mov_b32_e32 v3, v0
	v_mov_b32_e32 v4, v0
	v_mov_b32_e32 v5, v0
	v_mov_b32_e32 v6, v0
	v_mov_b32_e32 v7, v0
	v_mov_b32_e32 v8, v0
	v_mov_b32_e32 v9, v0
	v_mov_b32_e32 v10, v0
	v_mov_b32_e32 v11, v0
	v_mov_b32_e32 v12, v0
	v_mov_b32_e32 v13, v0
	v_mov_b32_e32 v14, v0
	v_mov_b32_e32 v15, v0
	v_mov_b32_e32 v32, v0
	v_mov_b32_e32 v33, v0
	v_mov_b32_e32 v34, v0
	v_mov_b32_e32 v35, v0
	v_mov_b32_e32 v36, v0
	v_mov_b32_e32 v37, v0
	v_mov_b32_e32 v38, v0
	v_mov_b32_e32 v39, v0
	v_mov_b32_e32 v40, v0
	v_mov_b32_e32 v41, v0
	v_mov_b32_e32 v42, v0
	v_mov_b32_e32 v43, v0
	v_mov_b32_e32 v44, v0
	v_mov_b32_e32 v45, v0
	v_mov_b32_e32 v46, v0
	v_mov_b32_e32 v47, v0
	v_mov_b32_e32 v16, v0
	v_mov_b32_e32 v17, v0
	v_mov_b32_e32 v18, v0
	v_mov_b32_e32 v19, v0
	v_mov_b32_e32 v20, v0
	v_mov_b32_e32 v21, v0
	v_mov_b32_e32 v22, v0
	v_mov_b32_e32 v23, v0
	v_mov_b32_e32 v24, v0
	v_mov_b32_e32 v25, v0
	v_mov_b32_e32 v26, v0
	v_mov_b32_e32 v27, v0
	v_mov_b32_e32 v28, v0
	v_mov_b32_e32 v29, v0
	v_mov_b32_e32 v30, v0
	v_mov_b32_e32 v31, v0
	v_mov_b32_e32 v48, v0
	v_mov_b32_e32 v49, v0
	v_mov_b32_e32 v50, v0
	v_mov_b32_e32 v51, v0
	v_mov_b32_e32 v52, v0
	v_mov_b32_e32 v53, v0
	v_mov_b32_e32 v54, v0
	v_mov_b32_e32 v55, v0
	v_mov_b32_e32 v56, v0
	v_mov_b32_e32 v57, v0
	v_mov_b32_e32 v58, v0
	v_mov_b32_e32 v59, v0
	v_mov_b32_e32 v60, v0
	v_mov_b32_e32 v61, v0
	v_mov_b32_e32 v62, v0
	v_mov_b32_e32 v63, v0
	s_waitcnt lgkmcnt(0)
	s_barrier

.LBB0_857:
	v_add_u32_e32 v2, s4, v0
	s_addk_i32 s4, 0x800
	v_mov_b32_e32 v222, v2
	v_ashrrev_i32_e32 v223, 31, v222
	v_lshlrev_b64 v[222:223], 2, v[222:223]
	v_lshl_add_u64 v[224:225], s[0:1], 0, v[222:223]
	global_load_dword v206, v[224:225], off
	global_load_dword v207, v[224:225], off offset:256
	v_lshl_add_u64 v[224:225], s[2:3], 0, v[222:223]
	global_load_dword v208, v[224:225], off
	global_load_dword v209, v[224:225], off offset:256
	v_add_u32_e32 v222, 0x200, v2
	v_ashrrev_i32_e32 v223, 31, v222
	v_lshlrev_b64 v[222:223], 2, v[222:223]
	v_lshl_add_u64 v[224:225], s[0:1], 0, v[222:223]
	global_load_dword v210, v[224:225], off
	global_load_dword v211, v[224:225], off offset:256
	v_lshl_add_u64 v[224:225], s[2:3], 0, v[222:223]
	global_load_dword v212, v[224:225], off
	global_load_dword v213, v[224:225], off offset:256
	v_add_u32_e32 v222, 0x400, v2
	v_ashrrev_i32_e32 v223, 31, v222
	v_lshlrev_b64 v[222:223], 2, v[222:223]
	v_lshl_add_u64 v[224:225], s[0:1], 0, v[222:223]
	global_load_dword v214, v[224:225], off
	global_load_dword v215, v[224:225], off offset:256
	v_lshl_add_u64 v[224:225], s[2:3], 0, v[222:223]
	global_load_dword v216, v[224:225], off
	global_load_dword v217, v[224:225], off offset:256
	v_add_u32_e32 v222, 0x600, v2
	v_ashrrev_i32_e32 v223, 31, v222
	v_lshlrev_b64 v[222:223], 2, v[222:223]
	v_lshl_add_u64 v[224:225], s[0:1], 0, v[222:223]
	global_load_dword v218, v[224:225], off
	global_load_dword v219, v[224:225], off offset:256
	v_lshl_add_u64 v[224:225], s[2:3], 0, v[222:223]
	global_load_dword v220, v[224:225], off
	global_load_dword v221, v[224:225], off offset:256
	v_add_u32_e32 v2, s4, v0
	s_addk_i32 s4, 0x800
	v_mov_b32_e32 v222, v2
	v_ashrrev_i32_e32 v223, 31, v222
	v_lshlrev_b64 v[222:223], 2, v[222:223]
	v_lshl_add_u64 v[224:225], s[0:1], 0, v[222:223]
	global_load_dword v10, v[224:225], off
	global_load_dword v11, v[224:225], off offset:256
	v_lshl_add_u64 v[224:225], s[2:3], 0, v[222:223]
	global_load_dword v12, v[224:225], off
	global_load_dword v13, v[224:225], off offset:256
	v_add_u32_e32 v222, 0x200, v2
	v_ashrrev_i32_e32 v223, 31, v222
	v_lshlrev_b64 v[222:223], 2, v[222:223]
	v_lshl_add_u64 v[224:225], s[0:1], 0, v[222:223]
	global_load_dword v14, v[224:225], off
	global_load_dword v15, v[224:225], off offset:256
	v_lshl_add_u64 v[224:225], s[2:3], 0, v[222:223]
	global_load_dword v16, v[224:225], off
	global_load_dword v17, v[224:225], off offset:256
	v_add_u32_e32 v222, 0x400, v2
	v_ashrrev_i32_e32 v223, 31, v222
	v_lshlrev_b64 v[222:223], 2, v[222:223]
	v_lshl_add_u64 v[224:225], s[0:1], 0, v[222:223]
	global_load_dword v18, v[224:225], off
	global_load_dword v19, v[224:225], off offset:256
	v_lshl_add_u64 v[224:225], s[2:3], 0, v[222:223]
	global_load_dword v20, v[224:225], off
	global_load_dword v21, v[224:225], off offset:256
	v_add_u32_e32 v222, 0x600, v2
	v_ashrrev_i32_e32 v223, 31, v222
	v_lshlrev_b64 v[222:223], 2, v[222:223]
	v_lshl_add_u64 v[224:225], s[0:1], 0, v[222:223]
	global_load_dword v22, v[224:225], off
	global_load_dword v23, v[224:225], off offset:256
	v_lshl_add_u64 v[224:225], s[2:3], 0, v[222:223]
	global_load_dword v24, v[224:225], off
	global_load_dword v25, v[224:225], off offset:256
	v_add_u32_e32 v9, 0x2400, v1
	s_waitcnt vmcnt(16)
	v_cvt_pk_bf16_f32 v226, v206, v207
	v_cvt_pk_bf16_f32 v230, v208, v209
	v_cvt_pk_bf16_f32 v227, v210, v211
	v_cvt_pk_bf16_f32 v231, v212, v213
	v_cvt_pk_bf16_f32 v228, v214, v215
	v_cvt_pk_bf16_f32 v232, v216, v217
	v_cvt_pk_bf16_f32 v229, v218, v219
	v_cvt_pk_bf16_f32 v233, v220, v221
	ds_write2_b32 v1, v226, v227 offset1:4
	ds_write2_b32 v9, v230, v231 offset1:4
	ds_write2_b32 v1, v228, v229 offset0:8 offset1:12
	ds_write2_b32 v9, v232, v233 offset0:8 offset1:12
	v_add_u32_e32 v1, 64, v1
	v_add_u32_e32 v9, 0x2400, v1
	s_waitcnt vmcnt(0)
	v_cvt_pk_bf16_f32 v226, v10, v11
	v_cvt_pk_bf16_f32 v230, v12, v13
	v_cvt_pk_bf16_f32 v227, v14, v15
	v_cvt_pk_bf16_f32 v231, v16, v17
	v_cvt_pk_bf16_f32 v228, v18, v19
	v_cvt_pk_bf16_f32 v232, v20, v21
	v_cvt_pk_bf16_f32 v229, v22, v23
	v_cvt_pk_bf16_f32 v233, v24, v25
	ds_write2_b32 v1, v226, v227 offset1:4
	ds_write2_b32 v9, v230, v231 offset1:4
	ds_write2_b32 v1, v228, v229 offset0:8 offset1:12
	ds_write2_b32 v9, v232, v233 offset0:8 offset1:12
	v_add_u32_e32 v1, 64, v1
	s_cmpk_eq_i32 s4, 0x1000
	v_and_b32_e32 v74, 31, v51
	v_mul_u32_u24_e32 v0, 0x48, v74
	v_lshrrev_b32_e32 v1, 1, v51
	v_lshlrev_b32_e32 v0, 1, v0
	v_and_b32_e32 v1, 16, v1
	s_movk_i32 s0, 0x1200
	v_add3_u32 v65, 0, v0, v1
	v_mov_b32_e32 v0, 0
	v_mul_lo_u32 v64, v66, s0
	s_mov_b32 s0, -16
	v_mov_b32_e32 v1, v0
	v_mov_b32_e32 v2, v0
	v_mov_b32_e32 v3, v0
	v_mov_b32_e32 v4, v0
	v_mov_b32_e32 v5, v0
	v_mov_b32_e32 v6, v0
	v_mov_b32_e32 v7, v0
	v_mov_b32_e32 v8, v0
	v_mov_b32_e32 v9, v0
	v_mov_b32_e32 v10, v0
	v_mov_b32_e32 v11, v0
	v_mov_b32_e32 v12, v0
	v_mov_b32_e32 v13, v0
	v_mov_b32_e32 v14, v0
	v_mov_b32_e32 v15, v0
	v_mov_b32_e32 v32, v0
	v_mov_b32_e32 v33, v0
	v_mov_b32_e32 v34, v0
	v_mov_b32_e32 v35, v0
	v_mov_b32_e32 v36, v0
	v_mov_b32_e32 v37, v0
	v_mov_b32_e32 v38, v0
	v_mov_b32_e32 v39, v0
	v_mov_b32_e32 v40, v0
	v_mov_b32_e32 v41, v0
	v_mov_b32_e32 v42, v0
	v_mov_b32_e32 v43, v0
	v_mov_b32_e32 v44, v0
	v_mov_b32_e32 v45, v0
	v_mov_b32_e32 v46, v0
	v_mov_b32_e32 v47, v0
	v_mov_b32_e32 v16, v0
	v_mov_b32_e32 v17, v0
	v_mov_b32_e32 v18, v0
	v_mov_b32_e32 v19, v0
	v_mov_b32_e32 v20, v0
	v_mov_b32_e32 v21, v0
	v_mov_b32_e32 v22, v0
	v_mov_b32_e32 v23, v0
	v_mov_b32_e32 v24, v0
	v_mov_b32_e32 v25, v0
	v_mov_b32_e32 v26, v0
	v_mov_b32_e32 v27, v0
	v_mov_b32_e32 v28, v0
	v_mov_b32_e32 v29, v0
	v_mov_b32_e32 v30, v0
	v_mov_b32_e32 v31, v0
	v_mov_b32_e32 v48, v0
	v_mov_b32_e32 v49, v0
	v_mov_b32_e32 v50, v0
	v_mov_b32_e32 v51, v0
	v_mov_b32_e32 v52, v0
	v_mov_b32_e32 v53, v0
	v_mov_b32_e32 v54, v0
	v_mov_b32_e32 v55, v0
	v_mov_b32_e32 v56, v0
	v_mov_b32_e32 v57, v0
	v_mov_b32_e32 v58, v0
	v_mov_b32_e32 v59, v0
	v_mov_b32_e32 v60, v0
	v_mov_b32_e32 v61, v0
	v_mov_b32_e32 v62, v0
	v_mov_b32_e32 v63, v0
	s_waitcnt lgkmcnt(0)
	s_barrier

.LBB0_906:
	v_add_u32_e32 v2, s38, v0
	s_addk_i32 s38, 0x800
	v_mov_b32_e32 v222, v2
	v_ashrrev_i32_e32 v223, 31, v222
	v_lshlrev_b64 v[222:223], 2, v[222:223]
	v_lshl_add_u64 v[224:225], s[0:1], 0, v[222:223]
	global_load_dword v206, v[224:225], off
	global_load_dword v207, v[224:225], off offset:256
	v_lshl_add_u64 v[224:225], s[2:3], 0, v[222:223]
	global_load_dword v208, v[224:225], off
	global_load_dword v209, v[224:225], off offset:256
	v_add_u32_e32 v222, 0x200, v2
	v_ashrrev_i32_e32 v223, 31, v222
	v_lshlrev_b64 v[222:223], 2, v[222:223]
	v_lshl_add_u64 v[224:225], s[0:1], 0, v[222:223]
	global_load_dword v210, v[224:225], off
	global_load_dword v211, v[224:225], off offset:256
	v_lshl_add_u64 v[224:225], s[2:3], 0, v[222:223]
	global_load_dword v212, v[224:225], off
	global_load_dword v213, v[224:225], off offset:256
	v_add_u32_e32 v222, 0x400, v2
	v_ashrrev_i32_e32 v223, 31, v222
	v_lshlrev_b64 v[222:223], 2, v[222:223]
	v_lshl_add_u64 v[224:225], s[0:1], 0, v[222:223]
	global_load_dword v214, v[224:225], off
	global_load_dword v215, v[224:225], off offset:256
	v_lshl_add_u64 v[224:225], s[2:3], 0, v[222:223]
	global_load_dword v216, v[224:225], off
	global_load_dword v217, v[224:225], off offset:256
	v_add_u32_e32 v222, 0x600, v2
	v_ashrrev_i32_e32 v223, 31, v222
	v_lshlrev_b64 v[222:223], 2, v[222:223]
	v_lshl_add_u64 v[224:225], s[0:1], 0, v[222:223]
	global_load_dword v218, v[224:225], off
	global_load_dword v219, v[224:225], off offset:256
	v_lshl_add_u64 v[224:225], s[2:3], 0, v[222:223]
	global_load_dword v220, v[224:225], off
	global_load_dword v221, v[224:225], off offset:256
	v_add_u32_e32 v2, s38, v0
	s_addk_i32 s38, 0x800
	v_mov_b32_e32 v222, v2
	v_ashrrev_i32_e32 v223, 31, v222
	v_lshlrev_b64 v[222:223], 2, v[222:223]
	v_lshl_add_u64 v[224:225], s[0:1], 0, v[222:223]
	global_load_dword v10, v[224:225], off
	global_load_dword v11, v[224:225], off offset:256
	v_lshl_add_u64 v[224:225], s[2:3], 0, v[222:223]
	global_load_dword v12, v[224:225], off
	global_load_dword v13, v[224:225], off offset:256
	v_add_u32_e32 v222, 0x200, v2
	v_ashrrev_i32_e32 v223, 31, v222
	v_lshlrev_b64 v[222:223], 2, v[222:223]
	v_lshl_add_u64 v[224:225], s[0:1], 0, v[222:223]
	global_load_dword v14, v[224:225], off
	global_load_dword v15, v[224:225], off offset:256
	v_lshl_add_u64 v[224:225], s[2:3], 0, v[222:223]
	global_load_dword v16, v[224:225], off
	global_load_dword v17, v[224:225], off offset:256
	v_add_u32_e32 v222, 0x400, v2
	v_ashrrev_i32_e32 v223, 31, v222
	v_lshlrev_b64 v[222:223], 2, v[222:223]
	v_lshl_add_u64 v[224:225], s[0:1], 0, v[222:223]
	global_load_dword v18, v[224:225], off
	global_load_dword v19, v[224:225], off offset:256
	v_lshl_add_u64 v[224:225], s[2:3], 0, v[222:223]
	global_load_dword v20, v[224:225], off
	global_load_dword v21, v[224:225], off offset:256
	v_add_u32_e32 v222, 0x600, v2
	v_ashrrev_i32_e32 v223, 31, v222
	v_lshlrev_b64 v[222:223], 2, v[222:223]
	v_lshl_add_u64 v[224:225], s[0:1], 0, v[222:223]
	global_load_dword v22, v[224:225], off
	global_load_dword v23, v[224:225], off offset:256
	v_lshl_add_u64 v[224:225], s[2:3], 0, v[222:223]
	global_load_dword v24, v[224:225], off
	global_load_dword v25, v[224:225], off offset:256
	v_add_u32_e32 v9, 0x2400, v1
	s_waitcnt vmcnt(16)
	v_cvt_pk_bf16_f32 v226, v206, v207
	v_cvt_pk_bf16_f32 v230, v208, v209
	v_cvt_pk_bf16_f32 v227, v210, v211
	v_cvt_pk_bf16_f32 v231, v212, v213
	v_cvt_pk_bf16_f32 v228, v214, v215
	v_cvt_pk_bf16_f32 v232, v216, v217
	v_cvt_pk_bf16_f32 v229, v218, v219
	v_cvt_pk_bf16_f32 v233, v220, v221
	ds_write2_b32 v1, v226, v227 offset1:4
	ds_write2_b32 v9, v230, v231 offset1:4
	ds_write2_b32 v1, v228, v229 offset0:8 offset1:12
	ds_write2_b32 v9, v232, v233 offset0:8 offset1:12
	v_add_u32_e32 v1, 64, v1
	v_add_u32_e32 v9, 0x2400, v1
	s_waitcnt vmcnt(0)
	v_cvt_pk_bf16_f32 v226, v10, v11
	v_cvt_pk_bf16_f32 v230, v12, v13
	v_cvt_pk_bf16_f32 v227, v14, v15
	v_cvt_pk_bf16_f32 v231, v16, v17
	v_cvt_pk_bf16_f32 v228, v18, v19
	v_cvt_pk_bf16_f32 v232, v20, v21
	v_cvt_pk_bf16_f32 v229, v22, v23
	v_cvt_pk_bf16_f32 v233, v24, v25
	ds_write2_b32 v1, v226, v227 offset1:4
	ds_write2_b32 v9, v230, v231 offset1:4
	ds_write2_b32 v1, v228, v229 offset0:8 offset1:12
	ds_write2_b32 v9, v232, v233 offset0:8 offset1:12
	v_add_u32_e32 v1, 64, v1
	s_cmpk_lg_i32 s38, 0x1000
	v_and_b32_e32 v145, 31, v51
	v_mul_u32_u24_e32 v0, 0x48, v145
	v_lshrrev_b32_e32 v1, 1, v51
	v_lshlrev_b32_e32 v0, 1, v0
	v_and_b32_e32 v1, 16, v1
	s_movk_i32 s0, 0x1200
	v_add3_u32 v135, 0, v0, v1
	v_mov_b32_e32 v0, 0
	v_mul_lo_u32 v134, v96, s0
	s_mov_b32 s0, -16
	v_mov_b32_e32 v1, v0
	v_mov_b32_e32 v2, v0
	v_mov_b32_e32 v3, v0
	v_mov_b32_e32 v4, v0
	v_mov_b32_e32 v5, v0
	v_mov_b32_e32 v6, v0
	v_mov_b32_e32 v7, v0
	v_mov_b32_e32 v8, v0
	v_mov_b32_e32 v9, v0
	v_mov_b32_e32 v10, v0
	v_mov_b32_e32 v11, v0
	v_mov_b32_e32 v12, v0
	v_mov_b32_e32 v13, v0
	v_mov_b32_e32 v14, v0
	v_mov_b32_e32 v15, v0
	v_mov_b32_e32 v32, v0
	v_mov_b32_e32 v33, v0
	v_mov_b32_e32 v34, v0
	v_mov_b32_e32 v35, v0
	v_mov_b32_e32 v36, v0
	v_mov_b32_e32 v37, v0
	v_mov_b32_e32 v38, v0
	v_mov_b32_e32 v39, v0
	v_mov_b32_e32 v40, v0
	v_mov_b32_e32 v41, v0
	v_mov_b32_e32 v42, v0
	v_mov_b32_e32 v43, v0
	v_mov_b32_e32 v44, v0
	v_mov_b32_e32 v45, v0
	v_mov_b32_e32 v46, v0
	v_mov_b32_e32 v47, v0
	v_mov_b32_e32 v16, v0
	v_mov_b32_e32 v17, v0
	v_mov_b32_e32 v18, v0
	v_mov_b32_e32 v19, v0
	v_mov_b32_e32 v20, v0
	v_mov_b32_e32 v21, v0
	v_mov_b32_e32 v22, v0
	v_mov_b32_e32 v23, v0
	v_mov_b32_e32 v24, v0
	v_mov_b32_e32 v25, v0
	v_mov_b32_e32 v26, v0
	v_mov_b32_e32 v27, v0
	v_mov_b32_e32 v28, v0
	v_mov_b32_e32 v29, v0
	v_mov_b32_e32 v30, v0
	v_mov_b32_e32 v31, v0
	v_mov_b32_e32 v48, v0
	v_mov_b32_e32 v49, v0
	v_mov_b32_e32 v50, v0
	v_mov_b32_e32 v51, v0
	v_mov_b32_e32 v52, v0
	v_mov_b32_e32 v53, v0
	v_mov_b32_e32 v54, v0
	v_mov_b32_e32 v55, v0
	v_mov_b32_e32 v56, v0
	v_mov_b32_e32 v57, v0
	v_mov_b32_e32 v58, v0
	v_mov_b32_e32 v59, v0
	v_mov_b32_e32 v60, v0
	v_mov_b32_e32 v61, v0
	v_mov_b32_e32 v62, v0
	v_mov_b32_e32 v63, v0
	s_waitcnt lgkmcnt(0)
	s_barrier

.LBB0_1296:
	v_min_i32_e32 v0, 0x4000, v12
	v_ashrrev_i32_e32 v0, 11, v0
	v_mul_hi_i32_i24_e32 v1, 0x9000, v0
	v_mul_i32_i24_e32 v0, 0x9000, v0
	v_lshl_add_u64 v[0:1], s[6:7], 0, v[0:1]
	v_lshl_add_u64 v[26:27], v[0:1], 0, s[16:17]
	v_lshl_add_u64 v[58:59], s[92:93], 0, v[20:21]
	v_lshl_add_u64 v[4:5], v[26:27], 0, v[96:97]
	v_lshl_add_u64 v[24:25], v[0:1], 0, v[96:97]
	global_load_dwordx4 v[38:41], v[58:59], off offset:16
	global_load_dwordx4 v[8:11], v[58:59], off
	global_load_dwordx4 v[42:45], v[16:17], off offset:16
	global_load_dwordx4 v[46:49], v[16:17], off
	global_load_dwordx4 v[50:53], v[24:25], off offset:16
	global_load_dwordx4 v[54:57], v[24:25], off
	global_load_dwordx4 v[0:3], v[4:5], off offset:16
	s_nop 0
	global_load_dwordx4 v[4:7], v[4:5], off
	v_mov_b32_e32 v23, v97
	v_lshl_add_u64 v[26:27], v[26:27], 0, v[22:23]
	v_lshl_add_u64 v[30:31], s[92:93], 0, v[18:19]
	v_add_u32_e32 v12, s8, v12
	v_lshl_add_u64 v[18:19], v[18:19], 0, s[30:31]
	v_lshl_add_u64 v[20:21], v[20:21], 0, s[14:15]
	s_waitcnt vmcnt(7)
	v_mov_b32_e32 v67, v39
	s_waitcnt vmcnt(6)
	v_mov_b32_e32 v66, v9
	v_pk_mul_f32 v[66:67], v[66:67], v[66:67]
	s_waitcnt vmcnt(1)
	v_pk_add_f32 v[60:61], v[0:1], 1.0 op_sel_hi:[1,0]
	s_waitcnt vmcnt(0)
	v_pk_add_f32 v[62:63], v[6:7], 1.0 op_sel_hi:[1,0]
	v_mov_b32_e32 v6, v8
	v_mov_b32_e32 v7, v38
	v_mov_b32_e32 v0, v10
	v_mov_b32_e32 v1, v40
	v_pk_fma_f32 v[6:7], v[6:7], v[6:7], v[66:67]
	v_pk_add_f32 v[64:65], v[4:5], 1.0 op_sel_hi:[1,0]
	v_mov_b32_e32 v4, v11
	v_mov_b32_e32 v5, v41
	v_pk_fma_f32 v[0:1], v[0:1], v[0:1], v[6:7]
	v_pk_add_f32 v[68:69], v[2:3], 1.0 op_sel_hi:[1,0]
	v_pk_fma_f32 v[66:67], v[4:5], v[4:5], v[0:1]
	global_load_dwordx4 v[0:3], v[58:59], off offset:2064
	global_load_dwordx4 v[4:7], v[58:59], off offset:2048
	global_load_dwordx4 v[86:89], v[14:15], off offset:16
	global_load_dwordx4 v[90:93], v[14:15], off
	global_load_dwordx4 v[98:101], v[24:25], off offset:2064
	global_load_dwordx4 v[106:109], v[24:25], off offset:2048
	global_load_dwordx4 v[110:113], v[26:27], off offset:16
	global_load_dwordx4 v[114:117], v[26:27], off
	v_add_f32_e32 v13, v66, v67
	s_waitcnt vmcnt(7)
	v_mov_b32_e32 v75, v1
	s_waitcnt vmcnt(6)
	v_mov_b32_e32 v74, v5
	v_mov_b32_e32 v72, v4
	v_mov_b32_e32 v73, v0
	v_pk_mul_f32 v[74:75], v[74:75], v[74:75]
	v_mov_b32_e32 v58, v6
	v_mov_b32_e32 v59, v2
	v_pk_fma_f32 v[72:73], v[72:73], v[72:73], v[74:75]
	v_mov_b32_e32 v70, v7
	v_mov_b32_e32 v71, v3
	v_pk_fma_f32 v[58:59], v[58:59], v[58:59], v[72:73]
	s_nop 0
	v_pk_fma_f32 v[58:59], v[70:71], v[70:71], v[58:59]
	s_nop 0
	v_add_f32_e32 v13, v13, v58
	v_add_f32_e32 v13, v13, v59
	v_mov_b32_e32 v23, v13
	v_mov_b32_e32 v255, v13
	s_nop 1
	v_permlane32_swap_b32_e32 v23, v255
	s_nop 1
	v_mov_b32_dpp v23, v255 quad_perm:[0,1,2,3] row_mask:0x3 bank_mask:0xf
	s_waitcnt lgkmcnt(0)
	v_add_f32_e32 v13, v13, v23
	v_mov_b32_e32 v23, v13
	v_mov_b32_e32 v255, v13
	s_nop 1
	v_permlane16_swap_b32_e32 v23, v255
	s_nop 1
	v_mov_b32_dpp v23, v255 quad_perm:[0,1,2,3] row_mask:0x5 bank_mask:0xf
	s_nop 0
	v_add_f32_e32 v13, v13, v23
	s_nop 1
	v_mov_b32_dpp v23, v13 row_ror:8 row_mask:0xf bank_mask:0xf
	s_nop 0
	v_add_f32_e32 v13, v13, v23
	s_nop 1
	v_mov_b32_dpp v23, v13 row_shl:4 row_mask:0xf bank_mask:0x5
	v_mov_b32_dpp v23, v13 row_shr:4 row_mask:0xf bank_mask:0xa
	s_nop 0
	v_add_f32_e32 v13, v13, v23
	s_nop 1
	v_mov_b32_dpp v23, v13 quad_perm:[2,3,0,1] row_mask:0xf bank_mask:0xf
	s_nop 0
	v_add_f32_e32 v13, v13, v23
	s_nop 1
	v_mov_b32_dpp v23, v13 quad_perm:[1,0,3,2] row_mask:0xf bank_mask:0xf
	s_nop 0
	v_add_f32_e32 v13, v13, v23
	v_fmamk_f32 v13, v13, 0x3a800000, v163
	v_cmp_gt_f32_e32 vcc, s86, v13
	v_mul_f32_e32 v23, 0x4b800000, v13
	s_nop 0
	v_cndmask_b32_e32 v13, v13, v23, vcc
	v_rsq_f32_e32 v13, v13
	s_nop 0
	v_mul_f32_e32 v23, 0x45800000, v13
	v_cndmask_b32_e32 v28, v13, v23, vcc
	v_pk_mul_f32 v[8:9], v[8:9], v[28:29] op_sel_hi:[1,0]
	v_pk_mul_f32 v[10:11], v[10:11], v[28:29] op_sel_hi:[1,0]
	v_pk_mul_f32 v[8:9], v[46:47], v[8:9]
	v_pk_mul_f32 v[10:11], v[48:49], v[10:11]
	v_pk_fma_f32 v[8:9], v[64:65], v[8:9], v[54:55]
	v_pk_fma_f32 v[10:11], v[62:63], v[10:11], v[56:57]
	v_cvt_pk_bf16_f32 v8, v8, v9
	v_cvt_pk_bf16_f32 v9, v10, v11
	v_pk_mul_f32 v[10:11], v[38:39], v[28:29] op_sel_hi:[1,0]
	v_pk_mul_f32 v[38:39], v[40:41], v[28:29] op_sel_hi:[1,0]
	v_pk_mul_f32 v[10:11], v[10:11], v[42:43]
	v_pk_mul_f32 v[38:39], v[38:39], v[44:45]
	v_pk_fma_f32 v[10:11], v[10:11], v[60:61], v[50:51]
	v_pk_fma_f32 v[38:39], v[38:39], v[68:69], v[52:53]
	v_add_co_u32_e32 v30, vcc, s28, v30
	v_cvt_pk_bf16_f32 v10, v10, v11
	v_cvt_pk_bf16_f32 v11, v38, v39
	v_addc_co_u32_e32 v31, vcc, 0, v31, vcc
	global_store_dwordx4 v[30:31], v[8:11], off
	s_nop 0
	s_nop 0
	v_pk_mul_f32 v[4:5], v[4:5], v[28:29] op_sel_hi:[1,0]
	v_pk_mul_f32 v[6:7], v[6:7], v[28:29] op_sel_hi:[1,0]
	v_pk_mul_f32 v[0:1], v[0:1], v[28:29] op_sel_hi:[1,0]
	v_pk_mul_f32 v[2:3], v[2:3], v[28:29] op_sel_hi:[1,0]
	v_cmp_le_i32_e32 vcc, s38, v12
	s_or_b64 s[12:13], vcc, s[12:13]
	s_waitcnt vmcnt(6)
	v_pk_mul_f32 v[0:1], v[0:1], v[86:87]
	s_waitcnt vmcnt(5)
	v_pk_mul_f32 v[4:5], v[4:5], v[90:91]
	v_pk_mul_f32 v[6:7], v[6:7], v[92:93]
	v_pk_mul_f32 v[2:3], v[2:3], v[88:89]
	s_waitcnt vmcnt(1)
	v_pk_add_f32 v[24:25], v[114:115], 1.0 op_sel_hi:[1,0]
	s_nop 0
	v_pk_fma_f32 v[4:5], v[4:5], v[24:25], v[106:107]
	v_pk_add_f32 v[24:25], v[116:117], 1.0 op_sel_hi:[1,0]
	v_cvt_pk_bf16_f32 v4, v4, v5
	v_pk_fma_f32 v[6:7], v[6:7], v[24:25], v[108:109]
	s_nop 0
	v_cvt_pk_bf16_f32 v5, v6, v7
	v_pk_add_f32 v[6:7], v[110:111], 1.0 op_sel_hi:[1,0]
	s_nop 0
	v_pk_fma_f32 v[0:1], v[0:1], v[6:7], v[98:99]
	v_pk_add_f32 v[6:7], v[112:113], 1.0 op_sel_hi:[1,0]
	s_nop 0
	v_pk_fma_f32 v[2:3], v[2:3], v[6:7], v[100:101]
	v_cvt_pk_bf16_f32 v6, v0, v1
	v_cvt_pk_bf16_f32 v7, v2, v3
	global_store_dwordx4 v[30:31], v[4:7], off offset:1024
	s_andn2_b64 exec, exec, s[12:13]
	s_cbranch_execnz .LBB0_1296
